# weight-conversion loops in out-proj phase: unrolled, all 32 loads of an item issued before LDS writes with counted vmcnt (was 2 loads per round trip)
# speedup vs baseline: 1.0402x; 1.0068x over previous
; #define LAS __attribute__((address_space(3)))
; __device__ __forceinline__ void transpose_item(const float* __restrict__ W, int K, int N, bf16* __restrict__ WT, int mode, LAS float* scr, int item, int lane) {
;     const int nblk = N / 32, kb = item / nblk, nb = item % nblk, k0 = 64 * kb, n0 = 32 * nb;
; #pragma unroll 8
;     for (int i = 0; i < 32; ++i) { const int kk = 2 * i + (lane >> 5); scr[kk * 33 + (lane & 31)] = __builtin_nontemporal_load(W + (size_t)(k0 + kk) * N + n0 + (lane & 31)); }
;     asm volatile("s_waitcnt lgkmcnt(0)" ::: "memory");
; __device__ __forceinline__ void convert_weights(ArgP A, unsigned char* lds_g, int gw, int NGW, int l0, int l1, int lane, int wave) {
;     ...
;     for (int it = l0 * PER_L + gw; it < l1 * PER_L; it += NGW) {
;         const int l = it / PER_L; int r = it - l * PER_L;
;         if (r < I_IN) { transpose_item(A->w_in + (size_t)l * DM * INW, DM, INW, (bf16*)(ws + WS_WIN) + (size_t)l * INW * DM, 1, scr, r, lane); continue; } r -= I_IN;
;         if (r < I_OUT) { transpose_item(A->w_out + (size_t)l * DM * DM, DM, DM, (bf16*)(ws + WS_WOUT) + (size_t)l * DM * DM, 0, scr, r, lane); continue; } r -= I_OUT;
;         if (r < I_F1) { transpose_item(A->w_ffn_in + (size_t)l * DM * FF2, DM, FF2, (bf16*)(ws + WS_WF1) + (size_t)l * FF2 * DM, 2, scr, r, lane); continue; } r -= I_F1;
;         transpose_item(A->w_ffn_out + (size_t)l * FFH * DM, FFH, DM, (bf16*)(ws + WS_WF2) + (size_t)l * DM * FFH, 0, scr, r, lane);
;     }
.LBB0_193:
	v_add_u32_e32 v12, s7, v8
	v_add_u32_e32 v10, 0xffffdf00, v12
	v_ashrrev_i32_e32 v11, 31, v10
	v_lshlrev_b64 v[10:11], 12, v[10:11]
	v_lshl_add_u64 v[10:11], v[6:7], 0, v[10:11]
	global_load_dword v172, v[10:11], off nt
	v_add_u32_e32 v10, 0xffffdf02, v12
	v_ashrrev_i32_e32 v11, 31, v10
	v_lshlrev_b64 v[10:11], 12, v[10:11]
	v_lshl_add_u64 v[10:11], v[6:7], 0, v[10:11]
	global_load_dword v173, v[10:11], off nt
	s_add_i32 s7, s7, 16
	v_add_u32_e32 v10, 0xffffdf04, v12
	v_ashrrev_i32_e32 v11, 31, v10
	v_lshlrev_b64 v[10:11], 12, v[10:11]
	v_lshl_add_u64 v[10:11], v[6:7], 0, v[10:11]
	global_load_dword v174, v[10:11], off nt
	v_add_u32_e32 v10, 0xffffdf06, v12
	v_ashrrev_i32_e32 v11, 31, v10
	v_lshlrev_b64 v[10:11], 12, v[10:11]
	v_lshl_add_u64 v[10:11], v[6:7], 0, v[10:11]
	global_load_dword v175, v[10:11], off nt
	v_add_u32_e32 v10, 0xffffdf08, v12
	v_ashrrev_i32_e32 v11, 31, v10
	v_lshlrev_b64 v[10:11], 12, v[10:11]
	v_lshl_add_u64 v[10:11], v[6:7], 0, v[10:11]
	global_load_dword v176, v[10:11], off nt
	v_add_u32_e32 v10, 0xffffdf0a, v12
	v_ashrrev_i32_e32 v11, 31, v10
	v_lshlrev_b64 v[10:11], 12, v[10:11]
	v_lshl_add_u64 v[10:11], v[6:7], 0, v[10:11]
	global_load_dword v177, v[10:11], off nt
	v_add_u32_e32 v10, 0xffffdf0c, v12
	v_ashrrev_i32_e32 v11, 31, v10
	v_lshlrev_b64 v[10:11], 12, v[10:11]
	v_lshl_add_u64 v[10:11], v[6:7], 0, v[10:11]
	global_load_dword v178, v[10:11], off nt
	v_add_u32_e32 v10, 0xffffdf0e, v12
	v_ashrrev_i32_e32 v11, 31, v10
	v_lshlrev_b64 v[10:11], 12, v[10:11]
	v_lshl_add_u64 v[10:11], v[6:7], 0, v[10:11]
	global_load_dword v179, v[10:11], off nt
	v_add_u32_e32 v12, s7, v8
	v_add_u32_e32 v10, 0xffffdf00, v12
	v_ashrrev_i32_e32 v11, 31, v10
	v_lshlrev_b64 v[10:11], 12, v[10:11]
	v_lshl_add_u64 v[10:11], v[6:7], 0, v[10:11]
	global_load_dword v180, v[10:11], off nt
	v_add_u32_e32 v10, 0xffffdf02, v12
	v_ashrrev_i32_e32 v11, 31, v10
	v_lshlrev_b64 v[10:11], 12, v[10:11]
	v_lshl_add_u64 v[10:11], v[6:7], 0, v[10:11]
	global_load_dword v181, v[10:11], off nt
	s_add_i32 s7, s7, 16
	v_add_u32_e32 v10, 0xffffdf04, v12
	v_ashrrev_i32_e32 v11, 31, v10
	v_lshlrev_b64 v[10:11], 12, v[10:11]
	v_lshl_add_u64 v[10:11], v[6:7], 0, v[10:11]
	global_load_dword v182, v[10:11], off nt
	v_add_u32_e32 v10, 0xffffdf06, v12
	v_ashrrev_i32_e32 v11, 31, v10
	v_lshlrev_b64 v[10:11], 12, v[10:11]
	v_lshl_add_u64 v[10:11], v[6:7], 0, v[10:11]
	global_load_dword v183, v[10:11], off nt
	v_add_u32_e32 v10, 0xffffdf08, v12
	v_ashrrev_i32_e32 v11, 31, v10
	v_lshlrev_b64 v[10:11], 12, v[10:11]
	v_lshl_add_u64 v[10:11], v[6:7], 0, v[10:11]
	global_load_dword v184, v[10:11], off nt
	v_add_u32_e32 v10, 0xffffdf0a, v12
	v_ashrrev_i32_e32 v11, 31, v10
	v_lshlrev_b64 v[10:11], 12, v[10:11]
	v_lshl_add_u64 v[10:11], v[6:7], 0, v[10:11]
	global_load_dword v185, v[10:11], off nt
	v_add_u32_e32 v10, 0xffffdf0c, v12
	v_ashrrev_i32_e32 v11, 31, v10
	v_lshlrev_b64 v[10:11], 12, v[10:11]
	v_lshl_add_u64 v[10:11], v[6:7], 0, v[10:11]
	global_load_dword v186, v[10:11], off nt
	v_add_u32_e32 v10, 0xffffdf0e, v12
	v_ashrrev_i32_e32 v11, 31, v10
	v_lshlrev_b64 v[10:11], 12, v[10:11]
	v_lshl_add_u64 v[10:11], v[6:7], 0, v[10:11]
	global_load_dword v187, v[10:11], off nt
	v_add_u32_e32 v12, s7, v8
	v_add_u32_e32 v10, 0xffffdf00, v12
	v_ashrrev_i32_e32 v11, 31, v10
	v_lshlrev_b64 v[10:11], 12, v[10:11]
	v_lshl_add_u64 v[10:11], v[6:7], 0, v[10:11]
	global_load_dword v188, v[10:11], off nt
	v_add_u32_e32 v10, 0xffffdf02, v12
	v_ashrrev_i32_e32 v11, 31, v10
	v_lshlrev_b64 v[10:11], 12, v[10:11]
	v_lshl_add_u64 v[10:11], v[6:7], 0, v[10:11]
	global_load_dword v189, v[10:11], off nt
	s_add_i32 s7, s7, 16
	v_add_u32_e32 v10, 0xffffdf04, v12
	v_ashrrev_i32_e32 v11, 31, v10
	v_lshlrev_b64 v[10:11], 12, v[10:11]
	v_lshl_add_u64 v[10:11], v[6:7], 0, v[10:11]
	global_load_dword v190, v[10:11], off nt
	v_add_u32_e32 v10, 0xffffdf06, v12
	v_ashrrev_i32_e32 v11, 31, v10
	v_lshlrev_b64 v[10:11], 12, v[10:11]
	v_lshl_add_u64 v[10:11], v[6:7], 0, v[10:11]
	global_load_dword v191, v[10:11], off nt
	v_add_u32_e32 v10, 0xffffdf08, v12
	v_ashrrev_i32_e32 v11, 31, v10
	v_lshlrev_b64 v[10:11], 12, v[10:11]
	v_lshl_add_u64 v[10:11], v[6:7], 0, v[10:11]
	global_load_dword v192, v[10:11], off nt
	v_add_u32_e32 v10, 0xffffdf0a, v12
	v_ashrrev_i32_e32 v11, 31, v10
	v_lshlrev_b64 v[10:11], 12, v[10:11]
	v_lshl_add_u64 v[10:11], v[6:7], 0, v[10:11]
	global_load_dword v193, v[10:11], off nt
	v_add_u32_e32 v10, 0xffffdf0c, v12
	v_ashrrev_i32_e32 v11, 31, v10
	v_lshlrev_b64 v[10:11], 12, v[10:11]
	v_lshl_add_u64 v[10:11], v[6:7], 0, v[10:11]
	global_load_dword v194, v[10:11], off nt
	v_add_u32_e32 v10, 0xffffdf0e, v12
	v_ashrrev_i32_e32 v11, 31, v10
	v_lshlrev_b64 v[10:11], 12, v[10:11]
	v_lshl_add_u64 v[10:11], v[6:7], 0, v[10:11]
	global_load_dword v195, v[10:11], off nt
	v_add_u32_e32 v12, s7, v8
	v_add_u32_e32 v10, 0xffffdf00, v12
	v_ashrrev_i32_e32 v11, 31, v10
	v_lshlrev_b64 v[10:11], 12, v[10:11]
	v_lshl_add_u64 v[10:11], v[6:7], 0, v[10:11]
	global_load_dword v196, v[10:11], off nt
	v_add_u32_e32 v10, 0xffffdf02, v12
	v_ashrrev_i32_e32 v11, 31, v10
	v_lshlrev_b64 v[10:11], 12, v[10:11]
	v_lshl_add_u64 v[10:11], v[6:7], 0, v[10:11]
	global_load_dword v197, v[10:11], off nt
	s_add_i32 s7, s7, 16
	v_add_u32_e32 v10, 0xffffdf04, v12
	v_ashrrev_i32_e32 v11, 31, v10
	v_lshlrev_b64 v[10:11], 12, v[10:11]
	v_lshl_add_u64 v[10:11], v[6:7], 0, v[10:11]
	global_load_dword v198, v[10:11], off nt
	v_add_u32_e32 v10, 0xffffdf06, v12
	v_ashrrev_i32_e32 v11, 31, v10
	v_lshlrev_b64 v[10:11], 12, v[10:11]
	v_lshl_add_u64 v[10:11], v[6:7], 0, v[10:11]
	global_load_dword v199, v[10:11], off nt
	v_add_u32_e32 v10, 0xffffdf08, v12
	v_ashrrev_i32_e32 v11, 31, v10
	v_lshlrev_b64 v[10:11], 12, v[10:11]
	v_lshl_add_u64 v[10:11], v[6:7], 0, v[10:11]
	global_load_dword v218, v[10:11], off nt
	v_add_u32_e32 v10, 0xffffdf0a, v12
	v_ashrrev_i32_e32 v11, 31, v10
	v_lshlrev_b64 v[10:11], 12, v[10:11]
	v_lshl_add_u64 v[10:11], v[6:7], 0, v[10:11]
	global_load_dword v219, v[10:11], off nt
	v_add_u32_e32 v10, 0xffffdf0c, v12
	v_ashrrev_i32_e32 v11, 31, v10
	v_lshlrev_b64 v[10:11], 12, v[10:11]
	v_lshl_add_u64 v[10:11], v[6:7], 0, v[10:11]
	global_load_dword v220, v[10:11], off nt
	v_add_u32_e32 v10, 0xffffdf0e, v12
	v_ashrrev_i32_e32 v11, 31, v10
	v_lshlrev_b64 v[10:11], 12, v[10:11]
	v_lshl_add_u64 v[10:11], v[6:7], 0, v[10:11]
	global_load_dword v221, v[10:11], off nt
	v_add_u32_e32 v14, 0x400, v9
	s_waitcnt vmcnt(30)
; #define LAS __attribute__((address_space(3)))
; __device__ __forceinline__ unsigned pk2(float lo, float hi) { return pg8::cvt_pk_bf16(lo, hi); }
; __device__ __forceinline__ void transpose_item(const float* __restrict__ W, int K, int N, bf16* __restrict__ WT, int mode, LAS float* scr, int item, int lane) {
;     ...
;     for (int i = 0; i < 32; ++i) { const int kk = 2 * i + (lane >> 5); scr[kk * 33 + (lane & 31)] = __builtin_nontemporal_load(W + (size_t)(k0 + kk) * N + n0 + (lane & 31)); }
;     asm volatile("s_waitcnt lgkmcnt(0)" ::: "memory");
;     const int c = lane & 7; const int r0 = rowmap(mode, n0);
; #pragma unroll
;     for (int j = 0; j < 4; ++j) { const int n = (lane >> 3) + 8 * j; const LAS float* s = scr + (8 * c) * 33 + n;
;         u32x4 o; o.x = pk2(s[0 * 33], s[1 * 33]); o.y = pk2(s[2 * 33], s[3 * 33]); o.z = pk2(s[4 * 33], s[5 * 33]); o.w = pk2(s[6 * 33], s[7 * 33]);
;         *(u32x4*)(WT + (size_t)(r0 + n) * K + k0 + 8 * c) = o; }
;     asm volatile("s_waitcnt lgkmcnt(0)" ::: "memory");
	ds_write2_b32 v9, v172, v173 offset1:66
	s_waitcnt vmcnt(28)
	ds_write2_b32 v9, v174, v175 offset0:132 offset1:198
	v_add_u32_e32 v9, 0x840, v9
	s_waitcnt vmcnt(26)
	ds_write2_b32 v14, v176, v177 offset0:8 offset1:74
	s_waitcnt vmcnt(24)
	ds_write2_b32 v14, v178, v179 offset0:140 offset1:206
	v_add_u32_e32 v14, 0x400, v9
	s_waitcnt vmcnt(22)
	ds_write2_b32 v9, v180, v181 offset1:66
	s_waitcnt vmcnt(20)
	ds_write2_b32 v9, v182, v183 offset0:132 offset1:198
	v_add_u32_e32 v9, 0x840, v9
	s_waitcnt vmcnt(18)
	ds_write2_b32 v14, v184, v185 offset0:8 offset1:74
	s_waitcnt vmcnt(16)
	ds_write2_b32 v14, v186, v187 offset0:140 offset1:206
	v_add_u32_e32 v14, 0x400, v9
	s_waitcnt vmcnt(14)
	ds_write2_b32 v9, v188, v189 offset1:66
	s_waitcnt vmcnt(12)
	ds_write2_b32 v9, v190, v191 offset0:132 offset1:198
	v_add_u32_e32 v9, 0x840, v9
	s_waitcnt vmcnt(10)
	ds_write2_b32 v14, v192, v193 offset0:8 offset1:74
	s_waitcnt vmcnt(8)
	ds_write2_b32 v14, v194, v195 offset0:140 offset1:206
	v_add_u32_e32 v14, 0x400, v9
	s_waitcnt vmcnt(6)
	ds_write2_b32 v9, v196, v197 offset1:66
	s_waitcnt vmcnt(4)
	ds_write2_b32 v9, v198, v199 offset0:132 offset1:198
	v_add_u32_e32 v9, 0x840, v9
	s_waitcnt vmcnt(2)
	ds_write2_b32 v14, v218, v219 offset0:8 offset1:74
	s_waitcnt vmcnt(0)
	ds_write2_b32 v14, v220, v221 offset0:140 offset1:206
	s_lshl_b32 s7, s8, 1
	s_waitcnt lgkmcnt(0)
	s_andn2_b32 s7, s7, 63
	ds_read2_b32 v[8:9], v22 offset1:33
	s_add_i32 s72, s7, 0xffffdf00
	s_mul_i32 s22, s4, 0x580000
	s_waitcnt lgkmcnt(0)
	v_cvt_pk_bf16_f32 v8, v8, v9
	ds_read2_b32 v[10:11], v22 offset0:66 offset1:99
	s_mul_hi_i32 s7, s4, 0x580000
	s_add_u32 s25, s11, s22
	s_waitcnt lgkmcnt(0)
	v_cvt_pk_bf16_f32 v9, v10, v11
	ds_read2_b32 v[10:11], v22 offset0:132 offset1:165
	s_addc_u32 s7, s13, s7
	s_lshl_b64 s[22:23], s[72:73], 1
	s_waitcnt lgkmcnt(0)
	v_cvt_pk_bf16_f32 v10, v10, v11
	ds_read2_b32 v[12:13], v22 offset0:198 offset1:231
	s_add_u32 s22, s25, s22
	s_waitcnt lgkmcnt(0)
	v_cvt_pk_bf16_f32 v11, v12, v13
	v_or_b32_e32 v12, s6, v3
	s_addc_u32 s23, s7, s23
	v_lshlrev_b32_e32 v160, 1, v2
	v_mul_u32_u24_e32 v12, 0xb00, v12
	v_lshl_add_u64 v[6:7], s[22:23], 0, v[160:161]
	v_lshlrev_b32_e32 v160, 1, v12
	v_lshl_add_u64 v[12:13], v[6:7], 0, v[160:161]
	global_store_dwordx4 v[12:13], v[8:11], off
	ds_read2_b32 v[8:9], v22 offset0:8 offset1:41
	s_waitcnt lgkmcnt(0)
	v_cvt_pk_bf16_f32 v8, v8, v9
	ds_read2_b32 v[10:11], v22 offset0:74 offset1:107
	s_waitcnt lgkmcnt(0)
	v_cvt_pk_bf16_f32 v9, v10, v11
	ds_read2_b32 v[10:11], v22 offset0:140 offset1:173
	s_waitcnt lgkmcnt(0)
	v_cvt_pk_bf16_f32 v10, v10, v11
	ds_read2_b32 v[12:13], v22 offset0:206 offset1:239
	s_waitcnt lgkmcnt(0)
	v_cvt_pk_bf16_f32 v11, v12, v13
	v_or_b32_e32 v12, s6, v23
	v_mul_u32_u24_e32 v12, 0xb00, v12
	v_lshlrev_b32_e32 v160, 1, v12
	v_lshl_add_u64 v[12:13], v[6:7], 0, v[160:161]
	global_store_dwordx4 v[12:13], v[8:11], off
	ds_read2_b32 v[8:9], v22 offset0:16 offset1:49
	s_waitcnt lgkmcnt(0)
	v_cvt_pk_bf16_f32 v8, v8, v9
	ds_read2_b32 v[10:11], v22 offset0:82 offset1:115
	s_waitcnt lgkmcnt(0)
	v_cvt_pk_bf16_f32 v9, v10, v11
	ds_read2_b32 v[10:11], v22 offset0:148 offset1:181
	s_waitcnt lgkmcnt(0)
	v_cvt_pk_bf16_f32 v10, v10, v11
	ds_read2_b32 v[12:13], v22 offset0:214 offset1:247
	s_waitcnt lgkmcnt(0)
	v_cvt_pk_bf16_f32 v11, v12, v13
	v_or_b32_e32 v12, s6, v24
	v_mul_u32_u24_e32 v12, 0xb00, v12
	v_lshlrev_b32_e32 v160, 1, v12
	v_lshl_add_u64 v[12:13], v[6:7], 0, v[160:161]
	global_store_dwordx4 v[12:13], v[8:11], off
	ds_read2_b32 v[8:9], v22 offset0:24 offset1:57
	s_waitcnt lgkmcnt(0)
	v_cvt_pk_bf16_f32 v8, v8, v9
	ds_read2_b32 v[10:11], v22 offset0:90 offset1:123
	s_waitcnt lgkmcnt(0)
	v_cvt_pk_bf16_f32 v9, v10, v11
	ds_read2_b32 v[10:11], v22 offset0:156 offset1:189
	s_waitcnt lgkmcnt(0)
	v_cvt_pk_bf16_f32 v10, v10, v11
	ds_read2_b32 v[12:13], v22 offset0:222 offset1:255
	s_waitcnt lgkmcnt(0)
	v_cvt_pk_bf16_f32 v11, v12, v13
	v_or_b32_e32 v12, s6, v25
	v_mul_u32_u24_e32 v12, 0xb00, v12
	v_lshlrev_b32_e32 v160, 1, v12
	v_lshl_add_u64 v[6:7], v[6:7], 0, v[160:161]
	global_store_dwordx4 v[6:7], v[8:11], off
	s_waitcnt lgkmcnt(0)
	s_mov_b64 s[6:7], 0

; __device__ __forceinline__ void transpose_item(const float* __restrict__ W, int K, int N, bf16* __restrict__ WT, int mode, LAS float* scr, int item, int lane) {
;     const int nblk = N / 32, kb = item / nblk, nb = item % nblk, k0 = 64 * kb, n0 = 32 * nb;
; #pragma unroll 8
;     for (int i = 0; i < 32; ++i) { const int kk = 2 * i + (lane >> 5); scr[kk * 33 + (lane & 31)] = __builtin_nontemporal_load(W + (size_t)(k0 + kk) * N + n0 + (lane & 31)); }
;     asm volatile("s_waitcnt lgkmcnt(0)" ::: "memory");
.LBB0_197:
	v_lshl_add_u64 v[36:37], v[20:21], 0, s[6:7]
	global_load_dword v172, v[36:37], off nt
	v_lshl_add_u64 v[36:37], v[18:19], 0, s[6:7]
	global_load_dword v173, v[36:37], off nt
	v_lshl_add_u64 v[36:37], v[16:17], 0, s[6:7]
	global_load_dword v174, v[36:37], off nt
	v_lshl_add_u64 v[36:37], v[14:15], 0, s[6:7]
	global_load_dword v175, v[36:37], off nt
	v_lshl_add_u64 v[36:37], v[12:13], 0, s[6:7]
	global_load_dword v176, v[36:37], off nt
	v_lshl_add_u64 v[36:37], v[10:11], 0, s[6:7]
	global_load_dword v177, v[36:37], off nt
	v_lshl_add_u64 v[36:37], v[8:9], 0, s[6:7]
	global_load_dword v178, v[36:37], off nt
	v_lshl_add_u64 v[36:37], v[6:7], 0, s[6:7]
	global_load_dword v179, v[36:37], off nt
	s_add_u32 s6, s6, 0x58000
	s_addc_u32 s7, s7, 0
	v_lshl_add_u64 v[36:37], v[20:21], 0, s[6:7]
	global_load_dword v180, v[36:37], off nt
	v_lshl_add_u64 v[36:37], v[18:19], 0, s[6:7]
	global_load_dword v181, v[36:37], off nt
	v_lshl_add_u64 v[36:37], v[16:17], 0, s[6:7]
	global_load_dword v182, v[36:37], off nt
	v_lshl_add_u64 v[36:37], v[14:15], 0, s[6:7]
	global_load_dword v183, v[36:37], off nt
	v_lshl_add_u64 v[36:37], v[12:13], 0, s[6:7]
	global_load_dword v184, v[36:37], off nt
	v_lshl_add_u64 v[36:37], v[10:11], 0, s[6:7]
	global_load_dword v185, v[36:37], off nt
	v_lshl_add_u64 v[36:37], v[8:9], 0, s[6:7]
	global_load_dword v186, v[36:37], off nt
	v_lshl_add_u64 v[36:37], v[6:7], 0, s[6:7]
	global_load_dword v187, v[36:37], off nt
	s_add_u32 s6, s6, 0x58000
	s_addc_u32 s7, s7, 0
	v_lshl_add_u64 v[36:37], v[20:21], 0, s[6:7]
	global_load_dword v188, v[36:37], off nt
	v_lshl_add_u64 v[36:37], v[18:19], 0, s[6:7]
	global_load_dword v189, v[36:37], off nt
	v_lshl_add_u64 v[36:37], v[16:17], 0, s[6:7]
	global_load_dword v190, v[36:37], off nt
	v_lshl_add_u64 v[36:37], v[14:15], 0, s[6:7]
	global_load_dword v191, v[36:37], off nt
	v_lshl_add_u64 v[36:37], v[12:13], 0, s[6:7]
	global_load_dword v192, v[36:37], off nt
	v_lshl_add_u64 v[36:37], v[10:11], 0, s[6:7]
	global_load_dword v193, v[36:37], off nt
	v_lshl_add_u64 v[36:37], v[8:9], 0, s[6:7]
	global_load_dword v194, v[36:37], off nt
	v_lshl_add_u64 v[36:37], v[6:7], 0, s[6:7]
	global_load_dword v195, v[36:37], off nt
	s_add_u32 s6, s6, 0x58000
	s_addc_u32 s7, s7, 0
	v_lshl_add_u64 v[36:37], v[20:21], 0, s[6:7]
	global_load_dword v196, v[36:37], off nt
	v_lshl_add_u64 v[36:37], v[18:19], 0, s[6:7]
	global_load_dword v197, v[36:37], off nt
	v_lshl_add_u64 v[36:37], v[16:17], 0, s[6:7]
	global_load_dword v198, v[36:37], off nt
	v_lshl_add_u64 v[36:37], v[14:15], 0, s[6:7]
	global_load_dword v199, v[36:37], off nt
	v_lshl_add_u64 v[36:37], v[12:13], 0, s[6:7]
	global_load_dword v218, v[36:37], off nt
	v_lshl_add_u64 v[36:37], v[10:11], 0, s[6:7]
	global_load_dword v219, v[36:37], off nt
	v_lshl_add_u64 v[36:37], v[8:9], 0, s[6:7]
	global_load_dword v220, v[36:37], off nt
	v_lshl_add_u64 v[36:37], v[6:7], 0, s[6:7]
	global_load_dword v221, v[36:37], off nt
	s_add_u32 s6, s6, 0x58000
	s_addc_u32 s7, s7, 0
	v_add_u32_e32 v38, 0x400, v34
	s_waitcnt vmcnt(30)
	ds_write2_b32 v34, v172, v173 offset1:66
	s_waitcnt vmcnt(28)
	ds_write2_b32 v34, v174, v175 offset0:132 offset1:198
	v_add_u32_e32 v34, 0x840, v34
	s_waitcnt vmcnt(26)
	ds_write2_b32 v38, v176, v177 offset0:8 offset1:74
	s_waitcnt vmcnt(24)
	ds_write2_b32 v38, v178, v179 offset0:140 offset1:206
	v_add_u32_e32 v38, 0x400, v34
	s_waitcnt vmcnt(22)
	ds_write2_b32 v34, v180, v181 offset1:66
	s_waitcnt vmcnt(20)
	ds_write2_b32 v34, v182, v183 offset0:132 offset1:198
	v_add_u32_e32 v34, 0x840, v34
	s_waitcnt vmcnt(18)
	ds_write2_b32 v38, v184, v185 offset0:8 offset1:74
	s_waitcnt vmcnt(16)
; #define LAS __attribute__((address_space(3)))
; __device__ __forceinline__ unsigned pk2(float lo, float hi) { return pg8::cvt_pk_bf16(lo, hi); }
; __device__ __forceinline__ int rowmap(int mode, int n0) {
;     ...
;     if (mode == 2) { const int bj = n0 >= FFH ? 1 : 0, r = n0 - bj * FFH; return (r >> 7) * 256 + bj * 128 + (r & 127); }
; __device__ __forceinline__ void transpose_item(const float* __restrict__ W, int K, int N, bf16* __restrict__ WT, int mode, LAS float* scr, int item, int lane) {
;     ...
;     for (int i = 0; i < 32; ++i) { const int kk = 2 * i + (lane >> 5); scr[kk * 33 + (lane & 31)] = __builtin_nontemporal_load(W + (size_t)(k0 + kk) * N + n0 + (lane & 31)); }
;     asm volatile("s_waitcnt lgkmcnt(0)" ::: "memory");
;     const int c = lane & 7; const int r0 = rowmap(mode, n0);
; #pragma unroll
;     for (int j = 0; j < 4; ++j) { const int n = (lane >> 3) + 8 * j; const LAS float* s = scr + (8 * c) * 33 + n;
;         u32x4 o; o.x = pk2(s[0 * 33], s[1 * 33]); o.y = pk2(s[2 * 33], s[3 * 33]); o.z = pk2(s[4 * 33], s[5 * 33]); o.w = pk2(s[6 * 33], s[7 * 33]);
;         *(u32x4*)(WT + (size_t)(r0 + n) * K + k0 + 8 * c) = o; }
;     asm volatile("s_waitcnt lgkmcnt(0)" ::: "memory");
	ds_write2_b32 v38, v186, v187 offset0:140 offset1:206
	v_add_u32_e32 v38, 0x400, v34
	s_waitcnt vmcnt(14)
	ds_write2_b32 v34, v188, v189 offset1:66
	s_waitcnt vmcnt(12)
	ds_write2_b32 v34, v190, v191 offset0:132 offset1:198
	v_add_u32_e32 v34, 0x840, v34
	s_waitcnt vmcnt(10)
	ds_write2_b32 v38, v192, v193 offset0:8 offset1:74
	s_waitcnt vmcnt(8)
	ds_write2_b32 v38, v194, v195 offset0:140 offset1:206
	v_add_u32_e32 v38, 0x400, v34
	s_waitcnt vmcnt(6)
	ds_write2_b32 v34, v196, v197 offset1:66
	s_waitcnt vmcnt(4)
	ds_write2_b32 v34, v198, v199 offset0:132 offset1:198
	v_add_u32_e32 v34, 0x840, v34
	s_waitcnt vmcnt(2)
	ds_write2_b32 v38, v218, v219 offset0:8 offset1:74
	s_waitcnt vmcnt(0)
	ds_write2_b32 v38, v220, v221 offset0:140 offset1:206
	s_add_u32 s6, s14, s9
	s_addc_u32 s7, s15, s5
	s_and_b32 s5, 0xffff, s25
	s_and_b32 s9, 0xffff, s23
	s_cmpk_gt_u32 s9, 0x57
	s_cselect_b32 s9, 0xfffff500, 0
	s_waitcnt lgkmcnt(0)
	s_cselect_b32 s23, 0x80, 0
	s_add_i32 s9, s9, s5
	s_lshl_b32 s9, s9, 1
	s_and_b32 s5, s5, 0x60
	ds_read2_b32 v[8:9], v22 offset1:33
	s_and_b32 s9, s9, 0xffffff00
	s_or_b32 s5, s5, s23
	s_waitcnt lgkmcnt(0)
	v_cvt_pk_bf16_f32 v8, v8, v9
	ds_read2_b32 v[10:11], v22 offset0:66 offset1:99
	s_or_b32 s5, s5, s9
	s_and_b32 s9, 0xffff, s22
	s_waitcnt lgkmcnt(0)
	v_cvt_pk_bf16_f32 v9, v10, v11
	ds_read2_b32 v[10:11], v22 offset0:132 offset1:165
	s_lshl_b32 s9, s9, 1
	s_waitcnt lgkmcnt(0)
	v_cvt_pk_bf16_f32 v10, v10, v11
	ds_read2_b32 v[12:13], v22 offset0:198 offset1:231
	s_add_u32 s6, s6, s9
	s_waitcnt lgkmcnt(0)
	v_cvt_pk_bf16_f32 v11, v12, v13
	v_or_b32_e32 v12, s5, v3
	s_addc_u32 s7, s7, 0
	v_lshlrev_b32_e32 v160, 1, v2
	v_ashrrev_i32_e32 v13, 31, v12
	v_lshl_add_u64 v[6:7], s[6:7], 0, v[160:161]
	v_lshlrev_b64 v[12:13], 11, v[12:13]
	v_lshl_add_u64 v[12:13], v[6:7], 0, v[12:13]
	global_store_dwordx4 v[12:13], v[8:11], off
	ds_read2_b32 v[8:9], v22 offset0:8 offset1:41
	s_waitcnt lgkmcnt(0)
	v_cvt_pk_bf16_f32 v8, v8, v9
	ds_read2_b32 v[10:11], v22 offset0:74 offset1:107
	s_waitcnt lgkmcnt(0)
	v_cvt_pk_bf16_f32 v9, v10, v11
	ds_read2_b32 v[10:11], v22 offset0:140 offset1:173
	s_waitcnt lgkmcnt(0)
	v_cvt_pk_bf16_f32 v10, v10, v11
	ds_read2_b32 v[12:13], v22 offset0:206 offset1:239
	s_waitcnt lgkmcnt(0)
	v_cvt_pk_bf16_f32 v11, v12, v13
	v_or_b32_e32 v12, s5, v23
	v_ashrrev_i32_e32 v13, 31, v12
	v_lshlrev_b64 v[12:13], 11, v[12:13]
	v_lshl_add_u64 v[12:13], v[6:7], 0, v[12:13]
	global_store_dwordx4 v[12:13], v[8:11], off
	ds_read2_b32 v[8:9], v22 offset0:16 offset1:49
	s_waitcnt lgkmcnt(0)
	v_cvt_pk_bf16_f32 v8, v8, v9
	ds_read2_b32 v[10:11], v22 offset0:82 offset1:115
	s_waitcnt lgkmcnt(0)
	v_cvt_pk_bf16_f32 v9, v10, v11
	ds_read2_b32 v[10:11], v22 offset0:148 offset1:181
	s_waitcnt lgkmcnt(0)
	v_cvt_pk_bf16_f32 v10, v10, v11
	ds_read2_b32 v[12:13], v22 offset0:214 offset1:247
	s_waitcnt lgkmcnt(0)
	v_cvt_pk_bf16_f32 v11, v12, v13
	v_or_b32_e32 v12, s5, v24
	v_ashrrev_i32_e32 v13, 31, v12
	v_lshlrev_b64 v[12:13], 11, v[12:13]
	v_lshl_add_u64 v[12:13], v[6:7], 0, v[12:13]
	global_store_dwordx4 v[12:13], v[8:11], off
	ds_read2_b32 v[8:9], v22 offset0:24 offset1:57
	s_waitcnt lgkmcnt(0)
	v_cvt_pk_bf16_f32 v8, v8, v9
	ds_read2_b32 v[10:11], v22 offset0:90 offset1:123
	s_waitcnt lgkmcnt(0)
	v_cvt_pk_bf16_f32 v9, v10, v11
	ds_read2_b32 v[10:11], v22 offset0:156 offset1:189
	s_waitcnt lgkmcnt(0)
	v_cvt_pk_bf16_f32 v10, v10, v11
	ds_read2_b32 v[12:13], v22 offset0:222 offset1:255
	s_waitcnt lgkmcnt(0)
	v_cvt_pk_bf16_f32 v11, v12, v13
	v_or_b32_e32 v12, s5, v25
	v_ashrrev_i32_e32 v13, 31, v12
	v_lshlrev_b64 v[12:13], 11, v[12:13]
	v_lshl_add_u64 v[6:7], v[6:7], 0, v[12:13]
	global_store_dwordx4 v[6:7], v[8:11], off
	s_waitcnt lgkmcnt(0)

; __device__ __forceinline__ void transpose_item(const float* __restrict__ W, int K, int N, bf16* __restrict__ WT, int mode, LAS float* scr, int item, int lane) {
;     const int nblk = N / 32, kb = item / nblk, nb = item % nblk, k0 = 64 * kb, n0 = 32 * nb;
; #pragma unroll 8
;     for (int i = 0; i < 32; ++i) { const int kk = 2 * i + (lane >> 5); scr[kk * 33 + (lane & 31)] = __builtin_nontemporal_load(W + (size_t)(k0 + kk) * N + n0 + (lane & 31)); }
;     asm volatile("s_waitcnt lgkmcnt(0)" ::: "memory");
.LBB0_202:
	v_lshl_add_u64 v[36:37], v[20:21], 0, s[6:7]
	global_load_dword v172, v[36:37], off nt
	v_lshl_add_u64 v[36:37], v[18:19], 0, s[6:7]
	global_load_dword v173, v[36:37], off nt
	v_lshl_add_u64 v[36:37], v[16:17], 0, s[6:7]
	global_load_dword v174, v[36:37], off nt
	v_lshl_add_u64 v[36:37], v[14:15], 0, s[6:7]
	global_load_dword v175, v[36:37], off nt
	v_lshl_add_u64 v[36:37], v[12:13], 0, s[6:7]
	global_load_dword v176, v[36:37], off nt
	v_lshl_add_u64 v[36:37], v[10:11], 0, s[6:7]
	global_load_dword v177, v[36:37], off nt
	v_lshl_add_u64 v[36:37], v[8:9], 0, s[6:7]
	global_load_dword v178, v[36:37], off nt
	v_lshl_add_u64 v[36:37], v[6:7], 0, s[6:7]
	global_load_dword v179, v[36:37], off nt
	s_add_u32 s6, s6, 0x10000
	s_addc_u32 s7, s7, 0
	v_lshl_add_u64 v[36:37], v[20:21], 0, s[6:7]
	global_load_dword v180, v[36:37], off nt
	v_lshl_add_u64 v[36:37], v[18:19], 0, s[6:7]
	global_load_dword v181, v[36:37], off nt
	v_lshl_add_u64 v[36:37], v[16:17], 0, s[6:7]
	global_load_dword v182, v[36:37], off nt
	v_lshl_add_u64 v[36:37], v[14:15], 0, s[6:7]
	global_load_dword v183, v[36:37], off nt
	v_lshl_add_u64 v[36:37], v[12:13], 0, s[6:7]
	global_load_dword v184, v[36:37], off nt
	v_lshl_add_u64 v[36:37], v[10:11], 0, s[6:7]
	global_load_dword v185, v[36:37], off nt
	v_lshl_add_u64 v[36:37], v[8:9], 0, s[6:7]
	global_load_dword v186, v[36:37], off nt
	v_lshl_add_u64 v[36:37], v[6:7], 0, s[6:7]
	global_load_dword v187, v[36:37], off nt
	s_add_u32 s6, s6, 0x10000
	s_addc_u32 s7, s7, 0
	v_lshl_add_u64 v[36:37], v[20:21], 0, s[6:7]
	global_load_dword v188, v[36:37], off nt
	v_lshl_add_u64 v[36:37], v[18:19], 0, s[6:7]
	global_load_dword v189, v[36:37], off nt
	v_lshl_add_u64 v[36:37], v[16:17], 0, s[6:7]
	global_load_dword v190, v[36:37], off nt
	v_lshl_add_u64 v[36:37], v[14:15], 0, s[6:7]
	global_load_dword v191, v[36:37], off nt
	v_lshl_add_u64 v[36:37], v[12:13], 0, s[6:7]
	global_load_dword v192, v[36:37], off nt
	v_lshl_add_u64 v[36:37], v[10:11], 0, s[6:7]
	global_load_dword v193, v[36:37], off nt
	v_lshl_add_u64 v[36:37], v[8:9], 0, s[6:7]
	global_load_dword v194, v[36:37], off nt
	v_lshl_add_u64 v[36:37], v[6:7], 0, s[6:7]
	global_load_dword v195, v[36:37], off nt
	s_add_u32 s6, s6, 0x10000
	s_addc_u32 s7, s7, 0
	v_lshl_add_u64 v[36:37], v[20:21], 0, s[6:7]
	global_load_dword v196, v[36:37], off nt
	v_lshl_add_u64 v[36:37], v[18:19], 0, s[6:7]
	global_load_dword v197, v[36:37], off nt
	v_lshl_add_u64 v[36:37], v[16:17], 0, s[6:7]
	global_load_dword v198, v[36:37], off nt
	v_lshl_add_u64 v[36:37], v[14:15], 0, s[6:7]
	global_load_dword v199, v[36:37], off nt
	v_lshl_add_u64 v[36:37], v[12:13], 0, s[6:7]
	global_load_dword v218, v[36:37], off nt
	v_lshl_add_u64 v[36:37], v[10:11], 0, s[6:7]
	global_load_dword v219, v[36:37], off nt
	v_lshl_add_u64 v[36:37], v[8:9], 0, s[6:7]
	global_load_dword v220, v[36:37], off nt
	v_lshl_add_u64 v[36:37], v[6:7], 0, s[6:7]
	global_load_dword v221, v[36:37], off nt
	s_add_u32 s6, s6, 0x10000
	s_addc_u32 s7, s7, 0
	v_add_u32_e32 v38, 0x400, v34
	s_waitcnt vmcnt(30)
	ds_write2_b32 v34, v172, v173 offset1:66
	s_waitcnt vmcnt(28)
	ds_write2_b32 v34, v174, v175 offset0:132 offset1:198
	v_add_u32_e32 v34, 0x840, v34
	s_waitcnt vmcnt(26)
	ds_write2_b32 v38, v176, v177 offset0:8 offset1:74
	s_waitcnt vmcnt(24)
	ds_write2_b32 v38, v178, v179 offset0:140 offset1:206
	v_add_u32_e32 v38, 0x400, v34
	s_waitcnt vmcnt(22)
	ds_write2_b32 v34, v180, v181 offset1:66
	s_waitcnt vmcnt(20)
	ds_write2_b32 v34, v182, v183 offset0:132 offset1:198
	v_add_u32_e32 v34, 0x840, v34
	s_waitcnt vmcnt(18)
; #define LAS __attribute__((address_space(3)))
; __device__ __forceinline__ unsigned pk2(float lo, float hi) { return pg8::cvt_pk_bf16(lo, hi); }
; __device__ __forceinline__ void transpose_item(const float* __restrict__ W, int K, int N, bf16* __restrict__ WT, int mode, LAS float* scr, int item, int lane) {
;     ...
;     for (int i = 0; i < 32; ++i) { const int kk = 2 * i + (lane >> 5); scr[kk * 33 + (lane & 31)] = __builtin_nontemporal_load(W + (size_t)(k0 + kk) * N + n0 + (lane & 31)); }
;     asm volatile("s_waitcnt lgkmcnt(0)" ::: "memory");
;     const int c = lane & 7; const int r0 = rowmap(mode, n0);
; #pragma unroll
;     for (int j = 0; j < 4; ++j) { const int n = (lane >> 3) + 8 * j; const LAS float* s = scr + (8 * c) * 33 + n;
;         u32x4 o; o.x = pk2(s[0 * 33], s[1 * 33]); o.y = pk2(s[2 * 33], s[3 * 33]); o.z = pk2(s[4 * 33], s[5 * 33]); o.w = pk2(s[6 * 33], s[7 * 33]);
;         *(u32x4*)(WT + (size_t)(r0 + n) * K + k0 + 8 * c) = o; }
;     asm volatile("s_waitcnt lgkmcnt(0)" ::: "memory");
	ds_write2_b32 v38, v184, v185 offset0:8 offset1:74
	s_waitcnt vmcnt(16)
	ds_write2_b32 v38, v186, v187 offset0:140 offset1:206
	v_add_u32_e32 v38, 0x400, v34
	s_waitcnt vmcnt(14)
	ds_write2_b32 v34, v188, v189 offset1:66
	s_waitcnt vmcnt(12)
	ds_write2_b32 v34, v190, v191 offset0:132 offset1:198
	v_add_u32_e32 v34, 0x840, v34
	s_waitcnt vmcnt(10)
	ds_write2_b32 v38, v192, v193 offset0:8 offset1:74
	s_waitcnt vmcnt(8)
	ds_write2_b32 v38, v194, v195 offset0:140 offset1:206
	v_add_u32_e32 v38, 0x400, v34
	s_waitcnt vmcnt(6)
	ds_write2_b32 v34, v196, v197 offset1:66
	s_waitcnt vmcnt(4)
	ds_write2_b32 v34, v198, v199 offset0:132 offset1:198
	v_add_u32_e32 v34, 0x840, v34
	s_waitcnt vmcnt(2)
	ds_write2_b32 v38, v218, v219 offset0:8 offset1:74
	s_waitcnt vmcnt(0)
	ds_write2_b32 v38, v220, v221 offset0:140 offset1:206
	s_lshl_b32 s6, s8, 1
	s_add_i32 s6, s6, 0x1f900
	s_and_b32 s7, s6, 0x1ffc0
	s_lshl_b32 s6, s3, 5
	s_waitcnt lgkmcnt(0)
	s_and_b32 s6, s6, 0x3e0
	s_lshl_b64 s[22:23], s[4:5], 21
	ds_read2_b32 v[8:9], v22 offset1:33
	s_add_u32 s5, s16, s22
	s_waitcnt lgkmcnt(0)
	v_cvt_pk_bf16_f32 v8, v8, v9
	ds_read2_b32 v[10:11], v22 offset0:66 offset1:99
	s_addc_u32 s9, s17, s23
	s_lshl_b32 s7, s7, 1
	s_waitcnt lgkmcnt(0)
	v_cvt_pk_bf16_f32 v9, v10, v11
	ds_read2_b32 v[10:11], v22 offset0:132 offset1:165
	s_add_u32 s22, s5, s7
	s_waitcnt lgkmcnt(0)
	v_cvt_pk_bf16_f32 v10, v10, v11
	ds_read2_b32 v[12:13], v22 offset0:198 offset1:231
	s_addc_u32 s23, s9, 0
	v_lshlrev_b32_e32 v160, 1, v2
	s_waitcnt lgkmcnt(0)
	v_cvt_pk_bf16_f32 v11, v12, v13
	v_or_b32_e32 v12, s6, v3
	v_lshl_add_u64 v[6:7], s[22:23], 0, v[160:161]
	v_lshlrev_b32_e32 v160, 11, v12
	v_lshl_add_u64 v[12:13], v[6:7], 0, v[160:161]
	global_store_dwordx4 v[12:13], v[8:11], off
	ds_read2_b32 v[8:9], v22 offset0:8 offset1:41
	s_waitcnt lgkmcnt(0)
	v_cvt_pk_bf16_f32 v8, v8, v9
	ds_read2_b32 v[10:11], v22 offset0:74 offset1:107
	s_waitcnt lgkmcnt(0)
	v_cvt_pk_bf16_f32 v9, v10, v11
	ds_read2_b32 v[10:11], v22 offset0:140 offset1:173
	s_waitcnt lgkmcnt(0)
	v_cvt_pk_bf16_f32 v10, v10, v11
	ds_read2_b32 v[12:13], v22 offset0:206 offset1:239
	s_waitcnt lgkmcnt(0)
	v_cvt_pk_bf16_f32 v11, v12, v13
	v_or_b32_e32 v12, s6, v23
	v_lshlrev_b32_e32 v160, 11, v12
	v_lshl_add_u64 v[12:13], v[6:7], 0, v[160:161]
	global_store_dwordx4 v[12:13], v[8:11], off
	ds_read2_b32 v[8:9], v22 offset0:16 offset1:49
	s_waitcnt lgkmcnt(0)
	v_cvt_pk_bf16_f32 v8, v8, v9
	ds_read2_b32 v[10:11], v22 offset0:82 offset1:115
	s_waitcnt lgkmcnt(0)
	v_cvt_pk_bf16_f32 v9, v10, v11
	ds_read2_b32 v[10:11], v22 offset0:148 offset1:181
	s_waitcnt lgkmcnt(0)
	v_cvt_pk_bf16_f32 v10, v10, v11
	ds_read2_b32 v[12:13], v22 offset0:214 offset1:247
	s_waitcnt lgkmcnt(0)
	v_cvt_pk_bf16_f32 v11, v12, v13
	v_or_b32_e32 v12, s6, v24
	v_lshlrev_b32_e32 v160, 11, v12
	v_lshl_add_u64 v[12:13], v[6:7], 0, v[160:161]
	global_store_dwordx4 v[12:13], v[8:11], off
	ds_read2_b32 v[8:9], v22 offset0:24 offset1:57
	s_waitcnt lgkmcnt(0)
	v_cvt_pk_bf16_f32 v8, v8, v9
	ds_read2_b32 v[10:11], v22 offset0:90 offset1:123
	s_waitcnt lgkmcnt(0)
	v_cvt_pk_bf16_f32 v9, v10, v11
	ds_read2_b32 v[10:11], v22 offset0:156 offset1:189
	s_waitcnt lgkmcnt(0)
	v_cvt_pk_bf16_f32 v10, v10, v11
	ds_read2_b32 v[12:13], v22 offset0:222 offset1:255
	s_waitcnt lgkmcnt(0)
	v_cvt_pk_bf16_f32 v11, v12, v13
	v_or_b32_e32 v12, s6, v25
	v_lshlrev_b32_e32 v160, 11, v12
	v_lshl_add_u64 v[6:7], v[6:7], 0, v[160:161]
	global_store_dwordx4 v[6:7], v[8:11], off
	s_waitcnt lgkmcnt(0)

; __device__ __forceinline__ void transpose_item(const float* __restrict__ W, int K, int N, bf16* __restrict__ WT, int mode, LAS float* scr, int item, int lane) {
;     const int nblk = N / 32, kb = item / nblk, nb = item % nblk, k0 = 64 * kb, n0 = 32 * nb;
; #pragma unroll 8
;     for (int i = 0; i < 32; ++i) { const int kk = 2 * i + (lane >> 5); scr[kk * 33 + (lane & 31)] = __builtin_nontemporal_load(W + (size_t)(k0 + kk) * N + n0 + (lane & 31)); }
;     asm volatile("s_waitcnt lgkmcnt(0)" ::: "memory");
.LBB0_207:
	v_add_u32_e32 v12, s7, v8
	v_mad_i64_i32 v[10:11], s[22:23], v12, s59, v[6:7]
	global_load_dword v172, v[10:11], off nt
	v_add_u32_e32 v10, 2, v12
	v_mad_i64_i32 v[10:11], s[22:23], v10, s59, v[6:7]
	global_load_dword v173, v[10:11], off nt
	s_add_i32 s7, s7, 16
	v_add_u32_e32 v10, 4, v12
	v_mad_i64_i32 v[10:11], s[22:23], v10, s59, v[6:7]
	global_load_dword v174, v[10:11], off nt
	v_add_u32_e32 v10, 6, v12
	v_mad_i64_i32 v[10:11], s[22:23], v10, s59, v[6:7]
	global_load_dword v175, v[10:11], off nt
	v_add_u32_e32 v10, 8, v12
	v_mad_i64_i32 v[10:11], s[22:23], v10, s59, v[6:7]
	global_load_dword v176, v[10:11], off nt
	v_add_u32_e32 v10, 10, v12
	v_mad_i64_i32 v[10:11], s[22:23], v10, s59, v[6:7]
	global_load_dword v177, v[10:11], off nt
	v_add_u32_e32 v10, 12, v12
	v_mad_i64_i32 v[10:11], s[22:23], v10, s59, v[6:7]
	global_load_dword v178, v[10:11], off nt
	v_add_u32_e32 v10, 14, v12
	v_mad_i64_i32 v[10:11], s[22:23], v10, s59, v[6:7]
	global_load_dword v179, v[10:11], off nt
	v_add_u32_e32 v12, s7, v8
	v_mad_i64_i32 v[10:11], s[22:23], v12, s59, v[6:7]
	global_load_dword v180, v[10:11], off nt
	v_add_u32_e32 v10, 2, v12
	v_mad_i64_i32 v[10:11], s[22:23], v10, s59, v[6:7]
	global_load_dword v181, v[10:11], off nt
	s_add_i32 s7, s7, 16
	v_add_u32_e32 v10, 4, v12
	v_mad_i64_i32 v[10:11], s[22:23], v10, s59, v[6:7]
	global_load_dword v182, v[10:11], off nt
	v_add_u32_e32 v10, 6, v12
	v_mad_i64_i32 v[10:11], s[22:23], v10, s59, v[6:7]
	global_load_dword v183, v[10:11], off nt
	v_add_u32_e32 v10, 8, v12
	v_mad_i64_i32 v[10:11], s[22:23], v10, s59, v[6:7]
	global_load_dword v184, v[10:11], off nt
	v_add_u32_e32 v10, 10, v12
	v_mad_i64_i32 v[10:11], s[22:23], v10, s59, v[6:7]
	global_load_dword v185, v[10:11], off nt
	v_add_u32_e32 v10, 12, v12
	v_mad_i64_i32 v[10:11], s[22:23], v10, s59, v[6:7]
	global_load_dword v186, v[10:11], off nt
	v_add_u32_e32 v10, 14, v12
	v_mad_i64_i32 v[10:11], s[22:23], v10, s59, v[6:7]
	global_load_dword v187, v[10:11], off nt
	v_add_u32_e32 v12, s7, v8
	v_mad_i64_i32 v[10:11], s[22:23], v12, s59, v[6:7]
	global_load_dword v188, v[10:11], off nt
	v_add_u32_e32 v10, 2, v12
	v_mad_i64_i32 v[10:11], s[22:23], v10, s59, v[6:7]
	global_load_dword v189, v[10:11], off nt
	s_add_i32 s7, s7, 16
	v_add_u32_e32 v10, 4, v12
	v_mad_i64_i32 v[10:11], s[22:23], v10, s59, v[6:7]
	global_load_dword v190, v[10:11], off nt
	v_add_u32_e32 v10, 6, v12
	v_mad_i64_i32 v[10:11], s[22:23], v10, s59, v[6:7]
	global_load_dword v191, v[10:11], off nt
	v_add_u32_e32 v10, 8, v12
	v_mad_i64_i32 v[10:11], s[22:23], v10, s59, v[6:7]
	global_load_dword v192, v[10:11], off nt
	v_add_u32_e32 v10, 10, v12
	v_mad_i64_i32 v[10:11], s[22:23], v10, s59, v[6:7]
	global_load_dword v193, v[10:11], off nt
	v_add_u32_e32 v10, 12, v12
	v_mad_i64_i32 v[10:11], s[22:23], v10, s59, v[6:7]
	global_load_dword v194, v[10:11], off nt
	v_add_u32_e32 v10, 14, v12
	v_mad_i64_i32 v[10:11], s[22:23], v10, s59, v[6:7]
	global_load_dword v195, v[10:11], off nt
	v_add_u32_e32 v12, s7, v8
	v_mad_i64_i32 v[10:11], s[22:23], v12, s59, v[6:7]
	global_load_dword v196, v[10:11], off nt
	v_add_u32_e32 v10, 2, v12
	v_mad_i64_i32 v[10:11], s[22:23], v10, s59, v[6:7]
	global_load_dword v197, v[10:11], off nt
	s_add_i32 s7, s7, 16
	v_add_u32_e32 v10, 4, v12
	v_mad_i64_i32 v[10:11], s[22:23], v10, s59, v[6:7]
	global_load_dword v198, v[10:11], off nt
	v_add_u32_e32 v10, 6, v12
	v_mad_i64_i32 v[10:11], s[22:23], v10, s59, v[6:7]
	global_load_dword v199, v[10:11], off nt
	v_add_u32_e32 v10, 8, v12
	v_mad_i64_i32 v[10:11], s[22:23], v10, s59, v[6:7]
	global_load_dword v218, v[10:11], off nt
	v_add_u32_e32 v10, 10, v12
	v_mad_i64_i32 v[10:11], s[22:23], v10, s59, v[6:7]
	global_load_dword v219, v[10:11], off nt
	v_add_u32_e32 v10, 12, v12
	v_mad_i64_i32 v[10:11], s[22:23], v10, s59, v[6:7]
	global_load_dword v220, v[10:11], off nt
	v_add_u32_e32 v10, 14, v12
	v_mad_i64_i32 v[10:11], s[22:23], v10, s59, v[6:7]
	global_load_dword v221, v[10:11], off nt
	v_add_u32_e32 v14, 0x400, v9
	s_waitcnt vmcnt(30)
	ds_write2_b32 v9, v172, v173 offset1:66
	s_waitcnt vmcnt(28)
; #define LAS __attribute__((address_space(3)))
; __device__ __forceinline__ unsigned pk2(float lo, float hi) { return pg8::cvt_pk_bf16(lo, hi); }
; __device__ __forceinline__ int rowmap(int mode, int n0) {
;     if (mode == 1) { const int pn = n0 >> 8, q = n0 & 255; return pn * 256 + 128 * ((q & 63) >> 5) + 32 * (q >> 6); }
; __device__ __forceinline__ void transpose_item(const float* __restrict__ W, int K, int N, bf16* __restrict__ WT, int mode, LAS float* scr, int item, int lane) {
;     ...
;     for (int i = 0; i < 32; ++i) { const int kk = 2 * i + (lane >> 5); scr[kk * 33 + (lane & 31)] = __builtin_nontemporal_load(W + (size_t)(k0 + kk) * N + n0 + (lane & 31)); }
;     asm volatile("s_waitcnt lgkmcnt(0)" ::: "memory");
;     const int c = lane & 7; const int r0 = rowmap(mode, n0);
; #pragma unroll
;     for (int j = 0; j < 4; ++j) { const int n = (lane >> 3) + 8 * j; const LAS float* s = scr + (8 * c) * 33 + n;
;         u32x4 o; o.x = pk2(s[0 * 33], s[1 * 33]); o.y = pk2(s[2 * 33], s[3 * 33]); o.z = pk2(s[4 * 33], s[5 * 33]); o.w = pk2(s[6 * 33], s[7 * 33]);
;         *(u32x4*)(WT + (size_t)(r0 + n) * K + k0 + 8 * c) = o; }
;     asm volatile("s_waitcnt lgkmcnt(0)" ::: "memory");
; __device__ __forceinline__ void convert_weights(ArgP A, unsigned char* lds_g, int gw, int NGW, int l0, int l1, int lane, int wave) {
;     ...
;     for (int it = l0 * PER_L + gw; it < l1 * PER_L; it += NGW) {
;         const int l = it / PER_L; int r = it - l * PER_L;
;         if (r < I_IN) { transpose_item(A->w_in + (size_t)l * DM * INW, DM, INW, (bf16*)(ws + WS_WIN) + (size_t)l * INW * DM, 1, scr, r, lane); continue; } r -= I_IN;
;         if (r < I_OUT) { transpose_item(A->w_out + (size_t)l * DM * DM, DM, DM, (bf16*)(ws + WS_WOUT) + (size_t)l * DM * DM, 0, scr, r, lane); continue; } r -= I_OUT;
;         if (r < I_F1) { transpose_item(A->w_ffn_in + (size_t)l * DM * FF2, DM, FF2, (bf16*)(ws + WS_WF1) + (size_t)l * FF2 * DM, 2, scr, r, lane); continue; } r -= I_F1;
;         transpose_item(A->w_ffn_out + (size_t)l * FFH * DM, FFH, DM, (bf16*)(ws + WS_WF2) + (size_t)l * DM * FFH, 0, scr, r, lane);
;     }
	ds_write2_b32 v9, v174, v175 offset0:132 offset1:198
	v_add_u32_e32 v9, 0x840, v9
	s_waitcnt vmcnt(26)
	ds_write2_b32 v14, v176, v177 offset0:8 offset1:74
	s_waitcnt vmcnt(24)
	ds_write2_b32 v14, v178, v179 offset0:140 offset1:206
	v_add_u32_e32 v14, 0x400, v9
	s_waitcnt vmcnt(22)
	ds_write2_b32 v9, v180, v181 offset1:66
	s_waitcnt vmcnt(20)
	ds_write2_b32 v9, v182, v183 offset0:132 offset1:198
	v_add_u32_e32 v9, 0x840, v9
	s_waitcnt vmcnt(18)
	ds_write2_b32 v14, v184, v185 offset0:8 offset1:74
	s_waitcnt vmcnt(16)
	ds_write2_b32 v14, v186, v187 offset0:140 offset1:206
	v_add_u32_e32 v14, 0x400, v9
	s_waitcnt vmcnt(14)
	ds_write2_b32 v9, v188, v189 offset1:66
	s_waitcnt vmcnt(12)
	ds_write2_b32 v9, v190, v191 offset0:132 offset1:198
	v_add_u32_e32 v9, 0x840, v9
	s_waitcnt vmcnt(10)
	ds_write2_b32 v14, v192, v193 offset0:8 offset1:74
	s_waitcnt vmcnt(8)
	ds_write2_b32 v14, v194, v195 offset0:140 offset1:206
	v_add_u32_e32 v14, 0x400, v9
	s_waitcnt vmcnt(6)
	ds_write2_b32 v9, v196, v197 offset1:66
	s_waitcnt vmcnt(4)
	ds_write2_b32 v9, v198, v199 offset0:132 offset1:198
	v_add_u32_e32 v9, 0x840, v9
	s_waitcnt vmcnt(2)
	ds_write2_b32 v14, v218, v219 offset0:8 offset1:74
	s_waitcnt vmcnt(0)
	ds_write2_b32 v14, v220, v221 offset0:140 offset1:206
	s_mul_hi_i32 s7, s4, 0x380000
	s_mul_i32 s4, s4, 0x380000
	s_add_u32 s9, s28, s4
	s_addc_u32 s22, s29, s7
	s_waitcnt lgkmcnt(0)
	s_lshl_b32 s5, s5, 7
	s_and_b32 s4, s8, 0xffffff00
	s_and_b32 s5, s5, 0x80
	ds_read2_b32 v[8:9], v22 offset1:33
	s_or_b32 s4, s5, s4
	s_lshr_b32 s5, s8, 1
	s_waitcnt lgkmcnt(0)
	v_cvt_pk_bf16_f32 v8, v8, v9
	ds_read2_b32 v[10:11], v22 offset0:66 offset1:99
	s_and_b32 s5, s5, 0x60
	s_ashr_i32 s7, s6, 31
	s_waitcnt lgkmcnt(0)
	v_cvt_pk_bf16_f32 v9, v10, v11
	ds_read2_b32 v[10:11], v22 offset0:132 offset1:165
	s_or_b32 s4, s4, s5
	s_lshl_b64 s[6:7], s[6:7], 1
	s_waitcnt lgkmcnt(0)
	v_cvt_pk_bf16_f32 v10, v10, v11
	ds_read2_b32 v[12:13], v22 offset0:198 offset1:231
	s_add_u32 s6, s9, s6
	s_waitcnt lgkmcnt(0)
	v_cvt_pk_bf16_f32 v11, v12, v13
	v_or_b32_e32 v12, s4, v3
	s_addc_u32 s7, s22, s7
	v_lshlrev_b32_e32 v160, 1, v2
	v_ashrrev_i32_e32 v13, 31, v12
	v_lshl_add_u64 v[6:7], s[6:7], 0, v[160:161]
	v_lshlrev_b64 v[12:13], 11, v[12:13]
	v_lshl_add_u64 v[12:13], v[6:7], 0, v[12:13]
	global_store_dwordx4 v[12:13], v[8:11], off
	ds_read2_b32 v[8:9], v22 offset0:8 offset1:41
	s_waitcnt lgkmcnt(0)
	v_cvt_pk_bf16_f32 v8, v8, v9
	ds_read2_b32 v[10:11], v22 offset0:74 offset1:107
	s_waitcnt lgkmcnt(0)
	v_cvt_pk_bf16_f32 v9, v10, v11
	ds_read2_b32 v[10:11], v22 offset0:140 offset1:173
	s_waitcnt lgkmcnt(0)
	v_cvt_pk_bf16_f32 v10, v10, v11
	ds_read2_b32 v[12:13], v22 offset0:206 offset1:239
	s_waitcnt lgkmcnt(0)
	v_cvt_pk_bf16_f32 v11, v12, v13
	v_or_b32_e32 v12, s4, v23
	v_ashrrev_i32_e32 v13, 31, v12
	v_lshlrev_b64 v[12:13], 11, v[12:13]
	v_lshl_add_u64 v[12:13], v[6:7], 0, v[12:13]
	global_store_dwordx4 v[12:13], v[8:11], off
	ds_read2_b32 v[8:9], v22 offset0:16 offset1:49
	s_waitcnt lgkmcnt(0)
	v_cvt_pk_bf16_f32 v8, v8, v9
	ds_read2_b32 v[10:11], v22 offset0:82 offset1:115
	s_waitcnt lgkmcnt(0)
	v_cvt_pk_bf16_f32 v9, v10, v11
	ds_read2_b32 v[10:11], v22 offset0:148 offset1:181
	s_waitcnt lgkmcnt(0)
	v_cvt_pk_bf16_f32 v10, v10, v11
	ds_read2_b32 v[12:13], v22 offset0:214 offset1:247
	s_waitcnt lgkmcnt(0)
	v_cvt_pk_bf16_f32 v11, v12, v13
	v_or_b32_e32 v12, s4, v24
	v_ashrrev_i32_e32 v13, 31, v12
	v_lshlrev_b64 v[12:13], 11, v[12:13]
	v_lshl_add_u64 v[12:13], v[6:7], 0, v[12:13]
	global_store_dwordx4 v[12:13], v[8:11], off
	ds_read2_b32 v[8:9], v22 offset0:24 offset1:57
	s_waitcnt lgkmcnt(0)
	v_cvt_pk_bf16_f32 v8, v8, v9
	ds_read2_b32 v[10:11], v22 offset0:90 offset1:123
	s_waitcnt lgkmcnt(0)
	v_cvt_pk_bf16_f32 v9, v10, v11
	ds_read2_b32 v[10:11], v22 offset0:156 offset1:189
	s_waitcnt lgkmcnt(0)
	v_cvt_pk_bf16_f32 v10, v10, v11
	ds_read2_b32 v[12:13], v22 offset0:222 offset1:255
	s_waitcnt lgkmcnt(0)
	v_cvt_pk_bf16_f32 v11, v12, v13
	v_or_b32_e32 v12, s4, v25
	v_ashrrev_i32_e32 v13, 31, v12
	v_lshlrev_b64 v[12:13], 11, v[12:13]
	v_lshl_add_u64 v[6:7], v[6:7], 0, v[12:13]
	global_store_dwordx4 v[6:7], v[8:11], off
	s_waitcnt lgkmcnt(0)
	s_branch .LBB0_188
